# P8 (GroupNorm/merge) row loop: long-latency projection loads of column groups 1-3 issued at the row top; vmcnt waits re-derived per consumer
# baseline (speedup 1.0000x reference)
; __device__ __forceinline__ f32x4 unpack4(u32x2 u) { return (f32x4){__uint_as_float(u.x << 16), __uint_as_float(u.x & 0xffff0000u), __uint_as_float(u.y << 16), __uint_as_float(u.y & 0xffff0000u)}; }
; template <int ph>
; __device__ __forceinline__ void run_phase(const Args& args, LAS unsigned char* lds, const int G, const int bx, const bool fin = true) {
;     ...
;         for (int row = gw; row < MP; row += ngw) {
;             const int t = row & (T - 1); const int pbo = t > 0 ? -RP : 0; const float pm = t > 0 ? 1.f : 0.f;
;             POST_ROW(qr = unpack4(*(const u32x2*)(base + pbo)) * pm; qk = unpack4(*(const u32x2*)(base + pbo + 1024)) * pm; qv = unpack4(*(const u32x2*)(base + pbo + 2048)) * pm;)
.LBB0_1140:
	s_and_b32 s0, s42, 0x7ff
	v_lshl_add_u64 v[58:59], s[20:21], 0, v[56:57]
	s_cmp_eq_u32 s0, 0
	v_add_co_u32_e64 v90, s[0:1], s27, v58
	v_lshl_add_u64 v[64:65], s[24:25], 0, v[56:57]
	s_nop 0
	v_addc_co_u32_e64 v91, s[0:1], 0, v59, s[0:1]
	v_add_co_u32_e64 v86, s[0:1], s28, v58
	v_add_co_u32_e32 v60, vcc, 0x9e00000, v64
	s_nop 0
	v_addc_co_u32_e64 v87, s[0:1], 0, v59, s[0:1]
	v_add_co_u32_e64 v78, s[0:1], s38, v58
	v_addc_co_u32_e32 v61, vcc, 0, v65, vcc
	s_nop 0
	v_addc_co_u32_e64 v79, s[0:1], 0, v59, s[0:1]
	v_add_co_u32_e64 v80, s[0:1], s39, v58
	global_load_dwordx4 v[8:11], v[30:31], off
	global_load_dwordx4 v[12:15], v[32:33], off
	global_load_dwordx4 v[16:19], v[34:35], off
	v_addc_co_u32_e64 v81, s[0:1], 0, v59, s[0:1]
	v_add_co_u32_e64 v82, s[0:1], s40, v58
	global_load_dwordx4 v[24:27], v[36:37], off
	global_load_dwordx4 v[20:23], v[38:39], off
	global_load_dwordx4 v[0:3], v[40:41], off
	global_load_dwordx4 v[4:7], v[42:43], off
	v_addc_co_u32_e64 v83, s[0:1], 0, v59, s[0:1]
	v_add_co_u32_e64 v58, s[0:1], s41, v58
	global_load_dwordx2 v[76:77], v[90:91], off
	global_load_dwordx2 v[74:75], v[86:87], off
	global_load_dwordx2 v[72:73], v[78:79], off
	global_load_dwordx2 v[70:71], v[80:81], off
	global_load_dwordx2 v[68:69], v[82:83], off
	global_load_dwordx2 v[84:85], v[90:91], off offset:512
	global_load_dwordx2 v[88:89], v[86:87], off offset:512
	global_load_dwordx2 v[92:93], v[78:79], off offset:512
	global_load_dwordx2 v[94:95], v[80:81], off offset:512
	v_addc_co_u32_e64 v59, s[0:1], 0, v59, s[0:1]
	s_cselect_b64 s[0:1], -1, 0
	s_nop 0
	v_cndmask_b32_e64 v62, 1.0, 0, s[0:1]
	s_and_b64 s[0:1], s[0:1], exec
	global_load_dwordx2 v[96:97], v[82:83], off offset:512
	global_load_dwordx2 v[98:99], v[90:91], off offset:1024
	v_add_co_u32_e32 v66, vcc, s26, v64
	s_cselect_b32 s1, 0, -1
	s_cselect_b32 s0, 0, 0xffffe600
	global_load_dwordx2 v[112:113], v[90:91], off offset:1536
	s_nop 0
	global_load_dwordx2 v[90:91], v[86:87], off offset:1024
	s_nop 0
	global_load_dwordx2 v[86:87], v[86:87], off offset:1536
	s_nop 0
	global_load_dwordx2 v[114:115], v[78:79], off offset:1024
	global_load_dwordx2 v[134:135], v[78:79], off offset:1536
	global_load_dwordx2 v[136:137], v[80:81], off offset:1024
	global_load_dwordx2 v[140:141], v[80:81], off offset:1536
	global_load_dwordx2 v[142:143], v[82:83], off offset:1024
	global_load_dwordx2 v[144:145], v[82:83], off offset:1536
	v_addc_co_u32_e32 v67, vcc, 0, v65, vcc
	v_lshl_add_u64 v[64:65], v[64:65], 0, s[0:1]
	v_add_co_u32_e32 v78, vcc, s19, v64
	global_load_dwordx2 v[146:147], v[60:61], off
	global_load_dwordx2 v[148:149], v[60:61], off offset:2048
	v_addc_co_u32_e32 v79, vcc, 0, v65, vcc
	global_load_dwordx2 v[150:151], v[66:67], off
	global_load_dwordx2 v[152:153], v[78:79], off offset:2048
	v_add_co_u32_e32 v80, vcc, s26, v64
	s_add_i32 s42, s42, s18
	s_nop 0
	v_addc_co_u32_e32 v81, vcc, 0, v65, vcc
	global_load_dwordx2 v[154:155], v[80:81], off offset:-4096
	global_load_dwordx2 v[156:157], v[80:81], off
	global_load_dwordx2 v[188:189], v[60:61], off offset:512
	global_load_dwordx2 v[190:191], v[60:61], off offset:2560
	global_load_dwordx2 v[192:193], v[66:67], off offset:512
	global_load_dwordx2 v[194:195], v[78:79], off offset:512
	global_load_dwordx2 v[196:197], v[78:79], off offset:2560
	global_load_dwordx2 v[198:199], v[80:81], off offset:512
	global_load_dwordx2 v[200:201], v[60:61], off offset:1024
	global_load_dwordx2 v[204:205], v[60:61], off offset:3072
	global_load_dwordx2 v[206:207], v[66:67], off offset:1024
	global_load_dwordx2 v[208:209], v[78:79], off offset:1024
	global_load_dwordx2 v[210:211], v[78:79], off offset:3072
	global_load_dwordx2 v[212:213], v[80:81], off offset:1024
	global_load_dwordx2 v[214:215], v[60:61], off offset:1536
	global_load_dwordx2 v[216:217], v[60:61], off offset:3584
	global_load_dwordx2 v[218:219], v[66:67], off offset:1536
	global_load_dwordx2 v[220:221], v[78:79], off offset:1536
	global_load_dwordx2 v[222:223], v[78:79], off offset:3584
	global_load_dwordx2 v[224:225], v[80:81], off offset:1536
	s_add_u32 s20, s20, s22
	s_addc_u32 s21, s21, s23
	s_add_u32 s24, s24, s13
	s_addc_u32 s25, s25, s11
	s_cmpk_gt_i32 s42, 0x3fff
	s_waitcnt vmcnt(43)
	v_lshlrev_b32_e32 v160, 16, v77
	s_waitcnt vmcnt(42)
	v_lshlrev_b32_e32 v129, 16, v75
	v_lshlrev_b32_e32 v128, 16, v74
	v_and_b32_e32 v163, 0xffff0000, v75
	v_and_b32_e32 v162, 0xffff0000, v74
	v_and_b32_e32 v161, 0xffff0000, v77
	s_waitcnt vmcnt(38)
	v_lshlrev_b32_e32 v164, 16, v84
	v_and_b32_e32 v165, 0xffff0000, v84
	s_waitcnt vmcnt(37)
	v_lshlrev_b32_e32 v131, 16, v89
	v_lshlrev_b32_e32 v130, 16, v88
	v_and_b32_e32 v167, 0xffff0000, v89
	v_and_b32_e32 v166, 0xffff0000, v88
	v_pk_add_f32 v[178:179], v[128:129], v[162:163]
	s_waitcnt vmcnt(31)
	v_lshlrev_b32_e32 v133, 16, v91
	v_lshlrev_b32_e32 v108, 16, v96
	v_and_b32_e32 v109, 0xffff0000, v96
	v_lshlrev_b32_e32 v110, 16, v97
	v_and_b32_e32 v111, 0xffff0000, v97
	v_lshlrev_b32_e32 v168, 16, v98
	v_and_b32_e32 v169, 0xffff0000, v98
	v_lshlrev_b32_e32 v170, 16, v99
	v_and_b32_e32 v171, 0xffff0000, v99
	v_lshlrev_b32_e32 v132, 16, v90
	v_and_b32_e32 v173, 0xffff0000, v91
	v_and_b32_e32 v172, 0xffff0000, v90
	s_waitcnt vmcnt(25)
	v_lshlrev_b32_e32 v96, 16, v142
	v_and_b32_e32 v97, 0xffff0000, v142
	v_lshlrev_b32_e32 v98, 16, v143
	v_and_b32_e32 v99, 0xffff0000, v143
	v_lshlrev_b32_e32 v142, 16, v112
	v_and_b32_e32 v143, 0xffff0000, v112
	v_lshlrev_b32_e32 v83, 16, v87
	v_lshlrev_b32_e32 v82, 16, v86
	v_and_b32_e32 v177, 0xffff0000, v87
	v_and_b32_e32 v176, 0xffff0000, v86
	v_lshlrev_b32_e32 v100, 16, v92
	v_and_b32_e32 v101, 0xffff0000, v92
	v_lshlrev_b32_e32 v104, 16, v93
	v_and_b32_e32 v105, 0xffff0000, v93
	v_lshlrev_b32_e32 v102, 16, v94
	v_and_b32_e32 v103, 0xffff0000, v94
	v_lshlrev_b32_e32 v106, 16, v95
	v_and_b32_e32 v107, 0xffff0000, v95
	v_lshlrev_b32_e32 v88, 16, v114
	v_and_b32_e32 v89, 0xffff0000, v114
	v_lshlrev_b32_e32 v92, 16, v115
	v_and_b32_e32 v93, 0xffff0000, v115
	v_lshlrev_b32_e32 v90, 16, v136
	v_and_b32_e32 v91, 0xffff0000, v136
	v_lshlrev_b32_e32 v94, 16, v137
	v_and_b32_e32 v95, 0xffff0000, v137
	v_pk_add_f32 v[160:161], v[160:161], -1.0 op_sel_hi:[1,0]
	v_pk_add_f32 v[136:137], v[164:165], -1.0 op_sel_hi:[1,0]
	v_pk_add_f32 v[164:165], v[130:131], v[166:167]
	v_pk_add_f32 v[114:115], v[168:169], -1.0 op_sel_hi:[1,0]
	v_pk_add_f32 v[168:169], v[132:133], v[172:173]
	v_pk_add_f32 v[86:87], v[142:143], -1.0 op_sel_hi:[1,0]
	v_pk_add_f32 v[142:143], v[82:83], v[176:177]
	v_add_f32_e32 v139, v178, v179
	v_pk_fma_f32 v[26:27], v[26:27], v[160:161], 1.0 op_sel_hi:[1,1,0]
	v_add_f32_e32 v160, v164, v165
	v_add_f32_e32 v161, v168, v169
	v_add_f32_e32 v164, v142, v143
	v_add_f32_dpp v139, v139, v139 quad_perm:[1,0,3,2] row_mask:0xf bank_mask:0xf bound_ctrl:1
	v_lshlrev_b32_e32 v158, 16, v76
	v_and_b32_e32 v159, 0xffff0000, v76
	v_lshlrev_b32_e32 v116, 16, v72
	v_and_b32_e32 v117, 0xffff0000, v72
	v_lshlrev_b32_e32 v120, 16, v73
	v_and_b32_e32 v121, 0xffff0000, v73
	v_lshlrev_b32_e32 v124, 16, v68
	v_and_b32_e32 v125, 0xffff0000, v68
	v_lshlrev_b32_e32 v126, 16, v69
	v_and_b32_e32 v127, 0xffff0000, v69
	v_lshlrev_b32_e32 v68, 16, v140
	v_and_b32_e32 v69, 0xffff0000, v140
	v_lshlrev_b32_e32 v72, 16, v141
	v_and_b32_e32 v73, 0xffff0000, v141
	s_waitcnt vmcnt(24)
	v_lshlrev_b32_e32 v74, 16, v144
	v_and_b32_e32 v75, 0xffff0000, v144
	v_lshlrev_b32_e32 v76, 16, v145
	v_and_b32_e32 v77, 0xffff0000, v145
	s_waitcnt vmcnt(23)
	v_lshlrev_b32_e32 v140, 16, v146
	v_and_b32_e32 v141, 0xffff0000, v146
	v_lshlrev_b32_e32 v144, 16, v147
	v_and_b32_e32 v145, 0xffff0000, v147
	s_waitcnt vmcnt(22)
	v_lshlrev_b32_e32 v146, 16, v148
	v_and_b32_e32 v147, 0xffff0000, v148
	v_lshlrev_b32_e32 v148, 16, v149
	v_and_b32_e32 v149, 0xffff0000, v149
	v_add_f32_dpp v160, v160, v160 quad_perm:[1,0,3,2] row_mask:0xf bank_mask:0xf bound_ctrl:1
	v_add_f32_dpp v161, v161, v161 quad_perm:[1,0,3,2] row_mask:0xf bank_mask:0xf bound_ctrl:1
	v_add_f32_dpp v164, v164, v164 quad_perm:[1,0,3,2] row_mask:0xf bank_mask:0xf bound_ctrl:1
	v_add_f32_dpp v139, v139, v139 quad_perm:[2,3,0,1] row_mask:0xf bank_mask:0xf bound_ctrl:1
	v_lshlrev_b32_e32 v84, 16, v85
	v_and_b32_e32 v85, 0xffff0000, v85
	v_lshlrev_b32_e32 v174, 16, v113
	v_and_b32_e32 v175, 0xffff0000, v113
	v_xor_b32_e32 v183, 0x80000000, v149
	v_xor_b32_e32 v182, 0x80000000, v148
	v_xor_b32_e32 v185, 0x80000000, v147
	v_xor_b32_e32 v184, 0x80000000, v146
	v_add_f32_dpp v165, v160, v160 quad_perm:[2,3,0,1] row_mask:0xf bank_mask:0xf bound_ctrl:1
	v_add_f32_dpp v168, v161, v161 quad_perm:[2,3,0,1] row_mask:0xf bank_mask:0xf bound_ctrl:1
	v_add_f32_dpp v164, v164, v164 quad_perm:[2,3,0,1] row_mask:0xf bank_mask:0xf bound_ctrl:1
	s_waitcnt vmcnt(20)
	v_lshlrev_b32_e32 v160, 16, v152
	v_and_b32_e32 v161, 0xffff0000, v152
	v_lshlrev_b32_e32 v152, 16, v153
	v_and_b32_e32 v153, 0xffff0000, v153
	v_add_f32_dpp v139, v139, v139 row_half_mirror row_mask:0xf bank_mask:0xf bound_ctrl:1
	v_lshlrev_b32_e32 v118, 16, v70
	v_and_b32_e32 v119, 0xffff0000, v70
	v_lshlrev_b32_e32 v122, 16, v71
	v_and_b32_e32 v123, 0xffff0000, v71
	v_lshlrev_b32_e32 v64, 16, v134
	v_and_b32_e32 v65, 0xffff0000, v134
	v_lshlrev_b32_e32 v70, 16, v135
	v_and_b32_e32 v71, 0xffff0000, v135
	v_pk_add_f32 v[158:159], v[158:159], -1.0 op_sel_hi:[1,0]
	v_pk_add_f32 v[134:135], v[84:85], -1.0 op_sel_hi:[1,0]
	v_pk_add_f32 v[112:113], v[170:171], -1.0 op_sel_hi:[1,0]
	v_pk_add_f32 v[84:85], v[174:175], -1.0 op_sel_hi:[1,0]
	v_lshlrev_b32_e32 v170, 16, v150
	v_and_b32_e32 v171, 0xffff0000, v150
	v_lshlrev_b32_e32 v150, 16, v151
	v_and_b32_e32 v151, 0xffff0000, v151
	v_xor_b32_e32 v175, 0x80000000, v141
	v_xor_b32_e32 v174, 0x80000000, v140
	v_xor_b32_e32 v181, 0x80000000, v145
	v_xor_b32_e32 v180, 0x80000000, v144
	v_add_f32_dpp v178, v165, v165 row_half_mirror row_mask:0xf bank_mask:0xf bound_ctrl:1
	v_add_f32_dpp v179, v168, v168 row_half_mirror row_mask:0xf bank_mask:0xf bound_ctrl:1
	v_add_f32_dpp v186, v164, v164 row_half_mirror row_mask:0xf bank_mask:0xf bound_ctrl:1
	s_waitcnt vmcnt(19)
	v_lshlrev_b32_e32 v164, 16, v154
	v_and_b32_e32 v165, 0xffff0000, v154
	v_lshlrev_b32_e32 v154, 16, v155
	v_and_b32_e32 v155, 0xffff0000, v155
	v_pk_fma_f32 v[152:153], v[62:63], v[152:153], v[182:183] op_sel_hi:[0,1,1]
	v_pk_fma_f32 v[160:161], v[62:63], v[160:161], v[184:185] op_sel_hi:[0,1,1]
	v_add_f32_dpp v139, v139, v139 row_mirror row_mask:0xf bank_mask:0xf bound_ctrl:1
	v_pk_fma_f32 v[24:25], v[24:25], v[158:159], 1.0 op_sel_hi:[1,1,0]
	v_xor_b32_e32 v143, 0x80000000, v151
	v_xor_b32_e32 v142, 0x80000000, v150
	s_waitcnt vmcnt(18)
	v_lshlrev_b32_e32 v168, 16, v156
	v_and_b32_e32 v169, 0xffff0000, v156
	v_lshlrev_b32_e32 v156, 16, v157
	v_and_b32_e32 v157, 0xffff0000, v157
	v_add_f32_dpp v178, v178, v178 row_mirror row_mask:0xf bank_mask:0xf bound_ctrl:1
	v_add_f32_dpp v179, v179, v179 row_mirror row_mask:0xf bank_mask:0xf bound_ctrl:1
	v_pk_fma_f32 v[164:165], v[62:63], v[164:165], v[174:175] op_sel_hi:[0,1,1]
	v_pk_fma_f32 v[154:155], v[62:63], v[154:155], v[180:181] op_sel_hi:[0,1,1]
	v_pk_fma_f32 v[12:13], v[12:13], v[160:161], v[146:147]
	v_pk_fma_f32 v[14:15], v[14:15], v[152:153], v[148:149]
	v_fmac_f32_e32 v162, 0xbc800000, v139
	v_fmac_f32_e32 v163, 0xbc800000, v139
	v_fmac_f32_e32 v129, 0xbc800000, v139
	v_xor_b32_e32 v159, 0x80000000, v171
	v_xor_b32_e32 v158, 0x80000000, v170
	v_pk_fma_f32 v[142:143], v[62:63], v[156:157], v[142:143] op_sel_hi:[0,1,1]
	v_fmac_f32_e32 v128, 0xbc800000, v139
	v_fmac_f32_e32 v166, 0xbc800000, v178
	v_fmac_f32_e32 v167, 0xbc800000, v178
	v_fmac_f32_e32 v131, 0xbc800000, v178
	v_fmac_f32_e32 v172, 0xbc800000, v179
	v_fmac_f32_e32 v173, 0xbc800000, v179
	v_fmac_f32_e32 v133, 0xbc800000, v179
	v_pk_fma_f32 v[10:11], v[10:11], v[154:155], v[144:145]
	v_pk_fma_f32 v[140:141], v[8:9], v[164:165], v[140:141]
	v_pk_mul_f32 v[14:15], v[14:15], v[26:27]
	v_pk_mul_f32 v[12:13], v[12:13], v[24:25]
	v_mov_b32_e32 v24, v129
	v_mov_b32_e32 v25, v163
	v_mov_b32_e32 v129, v162
	v_add_f32_dpp v182, v186, v186 row_mirror row_mask:0xf bank_mask:0xf bound_ctrl:1
	v_pk_fma_f32 v[146:147], v[62:63], v[168:169], v[158:159] op_sel_hi:[0,1,1]
	v_fmac_f32_e32 v130, 0xbc800000, v178
	v_fmac_f32_e32 v132, 0xbc800000, v179
	v_pk_fma_f32 v[18:19], v[18:19], v[142:143], v[150:151]
	v_mov_b32_e32 v26, v131
	v_mov_b32_e32 v27, v167
	v_mov_b32_e32 v131, v166
	v_mov_b32_e32 v142, v133
	v_mov_b32_e32 v143, v173
	v_mov_b32_e32 v133, v172
	v_pk_mul_f32 v[12:13], v[140:141], v[12:13]
	v_pk_mul_f32 v[10:11], v[10:11], v[14:15]
	v_pk_mul_f32 v[14:15], v[24:25], v[24:25]
	v_pk_mul_f32 v[140:141], v[128:129], v[128:129]
	v_fmac_f32_e32 v176, 0xbc800000, v182
	v_fmac_f32_e32 v177, 0xbc800000, v182
	v_fmac_f32_e32 v83, 0xbc800000, v182
	v_pk_fma_f32 v[16:17], v[16:17], v[146:147], v[170:171]
	v_pk_mul_f32 v[144:145], v[26:27], v[26:27]
	v_pk_mul_f32 v[146:147], v[130:131], v[130:131]
	v_pk_mul_f32 v[148:149], v[142:143], v[142:143]
	v_pk_mul_f32 v[150:151], v[132:133], v[132:133]
	v_pk_mul_f32 v[10:11], v[22:23], v[10:11]
	v_pk_mul_f32 v[12:13], v[20:21], v[12:13]
	v_pk_mov_b32 v[20:21], v[140:141], v[14:15] op_sel:[1,0]
	v_mov_b32_e32 v141, v15
	v_fmac_f32_e32 v82, 0xbc800000, v182
	v_mov_b32_e32 v8, v83
	v_mov_b32_e32 v9, v177
	v_mov_b32_e32 v83, v176
	v_pk_mov_b32 v[14:15], v[146:147], v[144:145] op_sel:[1,0]
	v_mov_b32_e32 v147, v145
	v_pk_mov_b32 v[22:23], v[150:151], v[148:149] op_sel:[1,0]
	v_mov_b32_e32 v151, v149
	v_pk_mov_b32 v[148:149], v[12:13], v[10:11] op_sel:[1,0]
	v_mov_b32_e32 v13, v11
	v_pk_add_f32 v[10:11], v[20:21], v[140:141]
	v_pk_mul_f32 v[152:153], v[8:9], v[8:9]
	v_pk_mul_f32 v[154:155], v[82:83], v[82:83]
	v_pk_add_f32 v[14:15], v[14:15], v[146:147]
	v_pk_add_f32 v[20:21], v[22:23], v[150:151]
	v_pk_add_f32 v[12:13], v[148:149], v[12:13]
	v_add_f32_e32 v10, v10, v11
	v_pk_mov_b32 v[144:145], v[154:155], v[152:153] op_sel:[1,0]
	v_mov_b32_e32 v155, v153
	v_add_f32_e32 v11, v14, v15
	v_add_f32_e32 v14, v20, v21
	v_add_f32_e32 v12, v12, v13
	v_add_f32_dpp v10, v10, v10 quad_perm:[1,0,3,2] row_mask:0xf bank_mask:0xf bound_ctrl:1
	v_pk_add_f32 v[22:23], v[144:145], v[154:155]
	v_add_f32_dpp v13, v14, v14 quad_perm:[1,0,3,2] row_mask:0xf bank_mask:0xf bound_ctrl:1
	v_add_f32_dpp v12, v12, v12 quad_perm:[1,0,3,2] row_mask:0xf bank_mask:0xf bound_ctrl:1
	v_add_f32_dpp v10, v10, v10 quad_perm:[2,3,0,1] row_mask:0xf bank_mask:0xf bound_ctrl:1
	v_add_f32_e32 v15, v22, v23
	v_add_f32_dpp v11, v11, v11 quad_perm:[1,0,3,2] row_mask:0xf bank_mask:0xf bound_ctrl:1
	v_add_f32_dpp v13, v13, v13 quad_perm:[2,3,0,1] row_mask:0xf bank_mask:0xf bound_ctrl:1
	v_add_f32_dpp v12, v12, v12 quad_perm:[2,3,0,1] row_mask:0xf bank_mask:0xf bound_ctrl:1
	v_add_f32_dpp v10, v10, v10 row_half_mirror row_mask:0xf bank_mask:0xf bound_ctrl:1
	v_add_f32_dpp v14, v15, v15 quad_perm:[1,0,3,2] row_mask:0xf bank_mask:0xf bound_ctrl:1
	v_add_f32_dpp v11, v11, v11 quad_perm:[2,3,0,1] row_mask:0xf bank_mask:0xf bound_ctrl:1
	v_add_f32_dpp v13, v13, v13 row_half_mirror row_mask:0xf bank_mask:0xf bound_ctrl:1
	v_add_f32_dpp v12, v12, v12 row_half_mirror row_mask:0xf bank_mask:0xf bound_ctrl:1
	v_add_f32_dpp v15, v10, v10 row_mirror row_mask:0xf bank_mask:0xf bound_ctrl:1
	v_add_f32_dpp v11, v11, v11 row_half_mirror row_mask:0xf bank_mask:0xf bound_ctrl:1
	v_add_f32_dpp v13, v13, v13 row_mirror row_mask:0xf bank_mask:0xf bound_ctrl:1
	v_add_f32_dpp v10, v12, v12 row_mirror row_mask:0xf bank_mask:0xf bound_ctrl:1
	v_fmamk_f32 v12, v15, 0x3c800000, v29
	v_add_f32_dpp v14, v14, v14 quad_perm:[2,3,0,1] row_mask:0xf bank_mask:0xf bound_ctrl:1
	v_add_f32_dpp v11, v11, v11 row_mirror row_mask:0xf bank_mask:0xf bound_ctrl:1
	v_fmamk_f32 v13, v13, 0x3c800000, v29
	v_mul_f32_e32 v15, 0x4f800000, v12
	v_cmp_gt_f32_e64 s[4:5], s29, v12
	v_add_f32_dpp v14, v14, v14 row_half_mirror row_mask:0xf bank_mask:0xf bound_ctrl:1
	v_fmamk_f32 v11, v11, 0x3c800000, v29
	v_mul_f32_e32 v21, 0x4f800000, v13
	v_cmp_gt_f32_e64 s[0:1], s29, v13
	v_cndmask_b32_e64 v12, v12, v15, s[4:5]
	v_add_f32_dpp v14, v14, v14 row_mirror row_mask:0xf bank_mask:0xf bound_ctrl:1
	v_mul_f32_e32 v20, 0x4f800000, v11
	v_cmp_gt_f32_e32 vcc, s29, v11
	v_cndmask_b32_e64 v13, v13, v21, s[0:1]
	v_sqrt_f32_e32 v15, v12
	v_fmamk_f32 v14, v14, 0x3c800000, v29
	v_cndmask_b32_e32 v11, v11, v20, vcc
	v_sqrt_f32_e32 v21, v13
	v_mul_f32_e32 v22, 0x4f800000, v14
	v_cmp_gt_f32_e64 s[2:3], s29, v14
	v_sqrt_f32_e32 v20, v11
	v_add_u32_e32 v23, -1, v15
	v_cndmask_b32_e64 v14, v14, v22, s[2:3]
	v_sqrt_f32_e32 v22, v14
	v_add_u32_e32 v139, 1, v15
	v_add_u32_e32 v144, -1, v21
	v_fma_f32 v148, -v23, v15, v12
	v_add_u32_e32 v140, -1, v20
	v_add_u32_e32 v145, 1, v21
	v_fma_f32 v149, -v139, v15, v12
	v_fma_f32 v152, -v144, v21, v13
	v_cmp_ge_f32_e64 s[6:7], 0, v148
	v_add_u32_e32 v141, 1, v20
	v_fma_f32 v150, -v140, v20, v11
	v_fma_f32 v153, -v145, v21, v13
	v_cndmask_b32_e64 v15, v15, v23, s[6:7]
	v_cmp_ge_f32_e64 s[8:9], 0, v152
	v_cmp_lt_f32_e64 s[16:17], 0, v149
	v_add_u32_e32 v146, -1, v22
	v_fma_f32 v151, -v141, v20, v11
	v_cmp_ge_f32_e64 s[6:7], 0, v150
	v_cndmask_b32_e64 v21, v21, v144, s[8:9]
	v_cmp_lt_f32_e64 s[8:9], 0, v153
	v_cndmask_b32_e64 v15, v15, v139, s[16:17]
	v_add_u32_e32 v147, 1, v22
	v_fma_f32 v154, -v146, v22, v14
	v_cndmask_b32_e64 v20, v20, v140, s[6:7]
	v_cmp_lt_f32_e64 s[6:7], 0, v151
	v_cndmask_b32_e64 v21, v21, v145, s[8:9]
	v_mul_f32_e32 v23, 0x37800000, v15
	v_fma_f32 v155, -v147, v22, v14
	v_cmp_ge_f32_e64 s[14:15], 0, v154
	v_cndmask_b32_e64 v20, v20, v141, s[6:7]
	v_mul_f32_e32 v140, 0x37800000, v21
	v_cndmask_b32_e64 v15, v15, v23, s[4:5]
	v_cmp_class_f32_e64 s[4:5], v12, v138
	v_cndmask_b32_e64 v22, v22, v146, s[14:15]
	v_cmp_lt_f32_e64 s[14:15], 0, v155
	v_mul_f32_e32 v139, 0x37800000, v20
	v_cndmask_b32_e64 v21, v21, v140, s[0:1]
	v_cmp_class_f32_e64 s[0:1], v13, v138
	v_cndmask_b32_e64 v12, v15, v12, s[4:5]
	v_cndmask_b32_e64 v22, v22, v147, s[14:15]
	v_cndmask_b32_e32 v20, v20, v139, vcc
	v_cmp_class_f32_e32 vcc, v11, v138
	v_cndmask_b32_e64 v21, v21, v13, s[0:1]
	v_div_scale_f32 v13, s[0:1], v12, v12, 1.0
	v_mul_f32_e32 v141, 0x37800000, v22
	v_cndmask_b32_e32 v11, v20, v11, vcc
	v_rcp_f32_e32 v140, v13
	v_cndmask_b32_e64 v22, v22, v141, s[2:3]
	v_cmp_class_f32_e64 s[2:3], v14, v138
	v_div_scale_f32 v15, s[0:1], v11, v11, 1.0
	s_nop 0
	v_cndmask_b32_e64 v139, v22, v14, s[2:3]
	v_div_scale_f32 v22, s[2:3], v21, v21, 1.0
	v_rcp_f32_e32 v141, v15
	v_rcp_f32_e32 v144, v22
	v_fma_f32 v145, -v13, v140, 1.0
	v_div_scale_f32 v14, vcc, 1.0, v12, 1.0
	v_fmac_f32_e32 v140, v145, v140
	v_fma_f32 v146, -v15, v141, 1.0
	v_mul_f32_e32 v145, v14, v140
	v_div_scale_f32 v20, s[0:1], 1.0, v11, 1.0
	v_fma_f32 v147, -v22, v144, 1.0
	v_fmac_f32_e32 v141, v146, v141
	v_fma_f32 v148, -v13, v145, v14
	v_div_scale_f32 v23, s[4:5], 1.0, v21, 1.0
	v_fmac_f32_e32 v144, v147, v144
	v_mul_f32_e32 v146, v20, v141
	v_fmac_f32_e32 v145, v148, v140
	v_mul_f32_e32 v147, v23, v144
	v_fma_f32 v149, -v15, v146, v20
	v_fma_f32 v13, -v13, v145, v14
	v_fma_f32 v150, -v22, v147, v23
	v_fmac_f32_e32 v146, v149, v141
	v_div_fmas_f32 v13, v13, v140, v145
	v_fmac_f32_e32 v147, v150, v144
	v_fma_f32 v14, -v15, v146, v20
	v_div_fixup_f32 v12, v13, v12, 1.0
	s_mov_b64 vcc, s[0:1]
	v_fma_f32 v22, -v22, v147, v23
	v_div_fmas_f32 v20, v14, v141, v146
	v_pk_mul_f32 v[14:15], v[24:25], v[12:13] op_sel_hi:[1,0]
	v_pk_mul_f32 v[12:13], v[128:129], v[12:13] op_sel_hi:[1,0]
	s_mov_b64 vcc, s[4:5]
	v_div_fixup_f32 v20, v20, v11, 1.0
	v_div_fmas_f32 v11, v22, v144, v147
	v_pk_fma_f32 v[0:1], v[0:1], v[12:13], v[4:5]
	v_pk_fma_f32 v[2:3], v[2:3], v[14:15], v[6:7]
	v_pk_fma_f32 v[0:1], v[16:17], v[10:11], v[0:1] op_sel_hi:[1,0,1]
	v_pk_fma_f32 v[2:3], v[18:19], v[10:11], v[2:3] op_sel_hi:[1,0,1]
	v_pk_mul_f32 v[0:1], v[0:1], v[116:117]
	v_pk_mul_f32 v[2:3], v[2:3], v[120:121]
	v_pk_fma_f32 v[0:1], v[0:1], v[118:119], v[124:125]
	v_pk_fma_f32 v[2:3], v[2:3], v[122:123], v[126:127]
	v_cvt_pk_bf16_f32 v0, v0, v1
	v_cvt_pk_bf16_f32 v1, v2, v3
	v_div_fixup_f32 v4, v11, v21, 1.0
	global_store_dwordx2 v[58:59], v[0:1], off
	v_pk_mul_f32 v[26:27], v[26:27], v[20:21] op_sel_hi:[1,0]
	v_pk_mul_f32 v[128:129], v[130:131], v[20:21] op_sel_hi:[1,0]
	v_pk_mul_f32 v[130:131], v[142:143], v[4:5] op_sel_hi:[1,0]
	v_pk_mul_f32 v[132:133], v[132:133], v[4:5] op_sel_hi:[1,0]
	s_waitcnt vmcnt(18)
	v_mov_b64_e32 v[120:121], v[188:189]
	s_waitcnt vmcnt(17)
	v_mov_b64_e32 v[122:123], v[190:191]
	s_waitcnt vmcnt(16)
	v_mov_b64_e32 v[124:125], v[192:193]
	s_waitcnt vmcnt(15)
	v_mov_b64_e32 v[126:127], v[194:195]
	s_waitcnt vmcnt(14)
	v_mov_b64_e32 v[140:141], v[196:197]
	s_waitcnt vmcnt(13)
	v_mov_b64_e32 v[142:143], v[198:199]
	global_load_dwordx4 v[0:3], v[36:37], off offset:1024
	global_load_dwordx4 v[4:7], v[40:41], off offset:1024
	global_load_dwordx4 v[10:13], v[42:43], off offset:1024
	global_load_dwordx4 v[14:17], v[30:31], off offset:1024
	global_load_dwordx4 v[18:21], v[44:45], off
	global_load_dwordx4 v[22:25], v[46:47], off
	global_load_dwordx4 v[116:119], v[38:39], off offset:1024
	v_div_scale_f32 v156, s[2:3], v139, v139, 1.0
	v_rcp_f32_e32 v158, v156
	v_div_scale_f32 v157, s[2:3], 1.0, v139, 1.0
	s_mov_b64 vcc, s[2:3]
	v_fma_f32 v159, -v156, v158, 1.0
	v_fmac_f32_e32 v158, v159, v158
	v_lshlrev_b32_e32 v144, 16, v120
	v_and_b32_e32 v145, 0xffff0000, v120
	v_lshlrev_b32_e32 v120, 16, v121
	v_and_b32_e32 v121, 0xffff0000, v121
	v_lshlrev_b32_e32 v146, 16, v122
	v_and_b32_e32 v147, 0xffff0000, v122
	v_lshlrev_b32_e32 v122, 16, v123
	v_and_b32_e32 v123, 0xffff0000, v123
	v_lshlrev_b32_e32 v150, 16, v126
	v_and_b32_e32 v151, 0xffff0000, v126
	v_lshlrev_b32_e32 v126, 16, v127
	v_and_b32_e32 v127, 0xffff0000, v127
	v_lshlrev_b32_e32 v152, 16, v140
	v_and_b32_e32 v153, 0xffff0000, v140
	v_lshlrev_b32_e32 v140, 16, v141
	v_and_b32_e32 v141, 0xffff0000, v141
	s_waitcnt vmcnt(4)
	v_pk_fma_f32 v[4:5], v[4:5], v[128:129], v[10:11]
	v_pk_fma_f32 v[6:7], v[6:7], v[26:27], v[12:13]
	v_xor_b32_e32 v11, 0x80000000, v145
	v_xor_b32_e32 v10, 0x80000000, v144
	v_xor_b32_e32 v13, 0x80000000, v121
	v_xor_b32_e32 v12, 0x80000000, v120
	v_xor_b32_e32 v27, 0x80000000, v123
	v_xor_b32_e32 v26, 0x80000000, v122
	v_xor_b32_e32 v129, 0x80000000, v147
	v_xor_b32_e32 v128, 0x80000000, v146
	v_pk_fma_f32 v[10:11], v[62:63], v[150:151], v[10:11] op_sel_hi:[0,1,1]
	v_pk_fma_f32 v[12:13], v[62:63], v[126:127], v[12:13] op_sel_hi:[0,1,1]
	v_pk_fma_f32 v[26:27], v[62:63], v[140:141], v[26:27] op_sel_hi:[0,1,1]
	v_pk_fma_f32 v[126:127], v[62:63], v[152:153], v[128:129] op_sel_hi:[0,1,1]
	v_pk_fma_f32 v[0:1], v[0:1], v[136:137], 1.0 op_sel_hi:[1,1,0]
	v_pk_fma_f32 v[2:3], v[2:3], v[134:135], 1.0 op_sel_hi:[1,1,0]
	s_waitcnt vmcnt(3)
	v_pk_fma_f32 v[12:13], v[16:17], v[12:13], v[120:121]
	v_pk_fma_f32 v[10:11], v[14:15], v[10:11], v[144:145]
	s_waitcnt vmcnt(2)
	v_pk_fma_f32 v[14:15], v[18:19], v[126:127], v[146:147]
	v_pk_fma_f32 v[16:17], v[20:21], v[26:27], v[122:123]
	v_pk_mul_f32 v[0:1], v[14:15], v[0:1]
	v_pk_mul_f32 v[2:3], v[16:17], v[2:3]
	v_pk_mul_f32 v[0:1], v[10:11], v[0:1]
	v_pk_mul_f32 v[2:3], v[12:13], v[2:3]
	s_waitcnt vmcnt(0)
	v_pk_mul_f32 v[0:1], v[116:117], v[0:1]
	v_pk_mul_f32 v[2:3], v[118:119], v[2:3]
	v_lshlrev_b32_e32 v148, 16, v124
	v_pk_mov_b32 v[10:11], v[0:1], v[2:3] op_sel:[1,0]
	v_mov_b32_e32 v1, v3
	v_pk_add_f32 v[0:1], v[10:11], v[0:1]
	v_and_b32_e32 v149, 0xffff0000, v124
	v_add_f32_e32 v0, v0, v1
	v_lshlrev_b32_e32 v124, 16, v125
	v_and_b32_e32 v125, 0xffff0000, v125
	v_add_f32_dpp v0, v0, v0 quad_perm:[1,0,3,2] row_mask:0xf bank_mask:0xf bound_ctrl:1
	v_lshlrev_b32_e32 v154, 16, v142
	v_and_b32_e32 v155, 0xffff0000, v142
	v_lshlrev_b32_e32 v142, 16, v143
	v_and_b32_e32 v143, 0xffff0000, v143
	v_xor_b32_e32 v135, 0x80000000, v125
	v_xor_b32_e32 v134, 0x80000000, v124
	v_xor_b32_e32 v137, 0x80000000, v149
	v_xor_b32_e32 v136, 0x80000000, v148
	v_add_f32_dpp v0, v0, v0 quad_perm:[2,3,0,1] row_mask:0xf bank_mask:0xf bound_ctrl:1
	v_pk_fma_f32 v[128:129], v[62:63], v[142:143], v[134:135] op_sel_hi:[0,1,1]
	v_pk_fma_f32 v[134:135], v[62:63], v[154:155], v[136:137] op_sel_hi:[0,1,1]
	v_add_f32_dpp v0, v0, v0 row_half_mirror row_mask:0xf bank_mask:0xf bound_ctrl:1
	v_pk_fma_f32 v[18:19], v[22:23], v[134:135], v[148:149]
	v_pk_fma_f32 v[20:21], v[24:25], v[128:129], v[124:125]
	v_add_f32_dpp v0, v0, v0 row_mirror row_mask:0xf bank_mask:0xf bound_ctrl:1
	v_pk_fma_f32 v[2:3], v[20:21], v[0:1], v[6:7] op_sel_hi:[1,0,1]
	v_pk_fma_f32 v[0:1], v[18:19], v[0:1], v[4:5] op_sel_hi:[1,0,1]
	v_pk_mul_f32 v[2:3], v[2:3], v[104:105]
	v_pk_mul_f32 v[0:1], v[0:1], v[100:101]
	v_pk_fma_f32 v[2:3], v[2:3], v[106:107], v[110:111]
	v_pk_fma_f32 v[0:1], v[0:1], v[102:103], v[108:109]
	s_nop 0
	v_cvt_pk_bf16_f32 v0, v0, v1
	v_cvt_pk_bf16_f32 v1, v2, v3
	global_store_dwordx2 v[58:59], v[0:1], off offset:512
	v_mov_b64_e32 v[26:27], v[200:201]
	v_mov_b64_e32 v[104:105], v[204:205]
	v_mov_b64_e32 v[106:107], v[206:207]
	v_mov_b64_e32 v[108:109], v[208:209]
	v_mov_b64_e32 v[110:111], v[210:211]
	v_mov_b64_e32 v[116:117], v[212:213]
	global_load_dwordx4 v[0:3], v[36:37], off offset:2048
	global_load_dwordx4 v[4:7], v[40:41], off offset:2048
	global_load_dwordx4 v[10:13], v[42:43], off offset:2048
	global_load_dwordx4 v[14:17], v[30:31], off offset:2048
	global_load_dwordx4 v[18:21], v[48:49], off
	global_load_dwordx4 v[22:25], v[50:51], off
	global_load_dwordx4 v[100:103], v[38:39], off offset:2048
	v_lshlrev_b32_e32 v118, 16, v26
	v_and_b32_e32 v119, 0xffff0000, v26
	v_lshlrev_b32_e32 v26, 16, v27
	v_and_b32_e32 v27, 0xffff0000, v27
	v_lshlrev_b32_e32 v120, 16, v104
	v_and_b32_e32 v121, 0xffff0000, v104
	v_lshlrev_b32_e32 v104, 16, v105
	v_and_b32_e32 v105, 0xffff0000, v105
	v_lshlrev_b32_e32 v124, 16, v108
	v_and_b32_e32 v125, 0xffff0000, v108
	v_lshlrev_b32_e32 v108, 16, v109
	v_and_b32_e32 v109, 0xffff0000, v109
	v_lshlrev_b32_e32 v126, 16, v110
	v_and_b32_e32 v127, 0xffff0000, v110
	v_lshlrev_b32_e32 v110, 16, v111
	v_and_b32_e32 v111, 0xffff0000, v111
	s_waitcnt vmcnt(6)
	v_pk_fma_f32 v[0:1], v[0:1], v[114:115], 1.0 op_sel_hi:[1,1,0]
	v_pk_fma_f32 v[2:3], v[2:3], v[112:113], 1.0 op_sel_hi:[1,1,0]
	s_waitcnt vmcnt(4)
	v_pk_fma_f32 v[4:5], v[4:5], v[132:133], v[10:11]
	v_pk_fma_f32 v[6:7], v[6:7], v[130:131], v[12:13]
	v_xor_b32_e32 v11, 0x80000000, v119
	v_xor_b32_e32 v10, 0x80000000, v118
	v_xor_b32_e32 v13, 0x80000000, v27
	v_xor_b32_e32 v12, 0x80000000, v26
	v_xor_b32_e32 v113, 0x80000000, v105
	v_xor_b32_e32 v112, 0x80000000, v104
	v_xor_b32_e32 v115, 0x80000000, v121
	v_xor_b32_e32 v114, 0x80000000, v120
	v_pk_fma_f32 v[10:11], v[62:63], v[124:125], v[10:11] op_sel_hi:[0,1,1]
	v_pk_fma_f32 v[12:13], v[62:63], v[108:109], v[12:13] op_sel_hi:[0,1,1]
	v_pk_fma_f32 v[108:109], v[62:63], v[110:111], v[112:113] op_sel_hi:[0,1,1]
	v_pk_fma_f32 v[110:111], v[62:63], v[126:127], v[114:115] op_sel_hi:[0,1,1]
	s_waitcnt vmcnt(3)
	v_pk_fma_f32 v[12:13], v[16:17], v[12:13], v[26:27]
	v_pk_fma_f32 v[10:11], v[14:15], v[10:11], v[118:119]
	s_waitcnt vmcnt(2)
	v_pk_fma_f32 v[14:15], v[18:19], v[110:111], v[120:121]
	v_pk_fma_f32 v[16:17], v[20:21], v[108:109], v[104:105]
	v_pk_mul_f32 v[0:1], v[14:15], v[0:1]
	v_pk_mul_f32 v[2:3], v[16:17], v[2:3]
	v_pk_mul_f32 v[0:1], v[10:11], v[0:1]
	v_pk_mul_f32 v[2:3], v[12:13], v[2:3]
	s_waitcnt vmcnt(0)
; __device__ __forceinline__ f32x4 unpack4(u32x2 u) { return (f32x4){__uint_as_float(u.x << 16), __uint_as_float(u.x & 0xffff0000u), __uint_as_float(u.y << 16), __uint_as_float(u.y & 0xffff0000u)}; }
; template <int ph>
; __device__ __forceinline__ void run_phase(const Args& args, LAS unsigned char* lds, const int G, const int bx, const bool fin = true) {
;     ...
;         for (int row = gw; row < MP; row += ngw) {
;             const int t = row & (T - 1); const int pbo = t > 0 ? -RP : 0; const float pm = t > 0 ? 1.f : 0.f;
;             POST_ROW(qr = unpack4(*(const u32x2*)(base + pbo)) * pm; qk = unpack4(*(const u32x2*)(base + pbo + 1024)) * pm; qv = unpack4(*(const u32x2*)(base + pbo + 2048)) * pm;)
	v_pk_mul_f32 v[0:1], v[100:101], v[0:1]
	v_pk_mul_f32 v[2:3], v[102:103], v[2:3]
	v_lshlrev_b32_e32 v122, 16, v106
	v_pk_mov_b32 v[10:11], v[0:1], v[2:3] op_sel:[1,0]
	v_mov_b32_e32 v1, v3
	v_pk_add_f32 v[0:1], v[10:11], v[0:1]
	v_and_b32_e32 v123, 0xffff0000, v106
	v_add_f32_e32 v0, v0, v1
	v_lshlrev_b32_e32 v106, 16, v107
	v_and_b32_e32 v107, 0xffff0000, v107
	v_add_f32_dpp v0, v0, v0 quad_perm:[1,0,3,2] row_mask:0xf bank_mask:0xf bound_ctrl:1
	v_lshlrev_b32_e32 v128, 16, v116
	v_and_b32_e32 v129, 0xffff0000, v116
	v_lshlrev_b32_e32 v116, 16, v117
	v_and_b32_e32 v117, 0xffff0000, v117
	v_xor_b32_e32 v131, 0x80000000, v107
	v_xor_b32_e32 v130, 0x80000000, v106
	v_xor_b32_e32 v133, 0x80000000, v123
	v_xor_b32_e32 v132, 0x80000000, v122
	v_add_f32_dpp v0, v0, v0 quad_perm:[2,3,0,1] row_mask:0xf bank_mask:0xf bound_ctrl:1
	v_pk_fma_f32 v[112:113], v[62:63], v[116:117], v[130:131] op_sel_hi:[0,1,1]
	v_pk_fma_f32 v[114:115], v[62:63], v[128:129], v[132:133] op_sel_hi:[0,1,1]
	v_add_f32_dpp v0, v0, v0 row_half_mirror row_mask:0xf bank_mask:0xf bound_ctrl:1
	v_pk_fma_f32 v[18:19], v[22:23], v[114:115], v[122:123]
	v_pk_fma_f32 v[20:21], v[24:25], v[112:113], v[106:107]
	v_add_f32_dpp v0, v0, v0 row_mirror row_mask:0xf bank_mask:0xf bound_ctrl:1
	v_pk_fma_f32 v[2:3], v[20:21], v[0:1], v[6:7] op_sel_hi:[1,0,1]
	v_pk_fma_f32 v[0:1], v[18:19], v[0:1], v[4:5] op_sel_hi:[1,0,1]
	v_pk_mul_f32 v[2:3], v[2:3], v[92:93]
	v_pk_mul_f32 v[0:1], v[0:1], v[88:89]
	v_pk_fma_f32 v[2:3], v[2:3], v[94:95], v[98:99]
	v_pk_fma_f32 v[0:1], v[0:1], v[90:91], v[96:97]
	v_mul_f32_e32 v94, v157, v158
	v_cvt_pk_bf16_f32 v0, v0, v1
	v_cvt_pk_bf16_f32 v1, v2, v3
	global_store_dwordx2 v[58:59], v[0:1], off offset:1024
	v_mov_b64_e32 v[26:27], v[214:215]
	s_nop 0
	v_mov_b64_e32 v[60:61], v[216:217]
	s_nop 0
	v_mov_b64_e32 v[66:67], v[218:219]
	s_nop 0
	v_mov_b64_e32 v[88:89], v[220:221]
	v_mov_b64_e32 v[90:91], v[222:223]
	v_mov_b64_e32 v[92:93], v[224:225]
	global_load_dwordx4 v[0:3], v[36:37], off offset:3072
	global_load_dwordx4 v[4:7], v[40:41], off offset:3072
	global_load_dwordx4 v[10:13], v[42:43], off offset:3072
	global_load_dwordx4 v[14:17], v[30:31], off offset:3072
	global_load_dwordx4 v[18:21], v[52:53], off
	global_load_dwordx4 v[22:25], v[38:39], off offset:3072
	global_load_dwordx4 v[78:81], v[54:55], off
	v_fma_f32 v95, -v156, v94, v157
	v_fmac_f32_e32 v94, v95, v158
	v_fma_f32 v95, -v156, v94, v157
	v_div_fmas_f32 v94, v95, v158, v94
	v_div_fixup_f32 v94, v94, v139, 1.0
	v_pk_mul_f32 v[8:9], v[8:9], v[94:95] op_sel_hi:[1,0]
	v_pk_mul_f32 v[82:83], v[82:83], v[94:95] op_sel_hi:[1,0]
	v_lshlrev_b32_e32 v94, 16, v26
	v_and_b32_e32 v95, 0xffff0000, v26
	v_lshlrev_b32_e32 v96, 16, v60
	v_and_b32_e32 v97, 0xffff0000, v60
	v_lshlrev_b32_e32 v60, 16, v61
	v_and_b32_e32 v61, 0xffff0000, v61
	v_lshlrev_b32_e32 v26, 16, v27
	v_and_b32_e32 v27, 0xffff0000, v27
	v_lshlrev_b32_e32 v100, 16, v88
	v_and_b32_e32 v101, 0xffff0000, v88
	v_lshlrev_b32_e32 v102, 16, v90
	v_and_b32_e32 v103, 0xffff0000, v90
	v_lshlrev_b32_e32 v90, 16, v91
	v_and_b32_e32 v91, 0xffff0000, v91
	s_waitcnt vmcnt(4)
	v_pk_fma_f32 v[4:5], v[4:5], v[82:83], v[10:11]
	v_pk_fma_f32 v[6:7], v[6:7], v[8:9], v[12:13]
	v_xor_b32_e32 v9, 0x80000000, v95
	v_xor_b32_e32 v8, 0x80000000, v94
	v_xor_b32_e32 v13, 0x80000000, v61
	v_xor_b32_e32 v12, 0x80000000, v60
	v_xor_b32_e32 v83, 0x80000000, v97
	v_xor_b32_e32 v82, 0x80000000, v96
	v_lshlrev_b32_e32 v88, 16, v89
	v_and_b32_e32 v89, 0xffff0000, v89
	v_xor_b32_e32 v11, 0x80000000, v27
	v_xor_b32_e32 v10, 0x80000000, v26
	v_pk_fma_f32 v[8:9], v[62:63], v[100:101], v[8:9] op_sel_hi:[0,1,1]
	v_pk_fma_f32 v[12:13], v[62:63], v[90:91], v[12:13] op_sel_hi:[0,1,1]
	v_pk_fma_f32 v[82:83], v[62:63], v[102:103], v[82:83] op_sel_hi:[0,1,1]
	v_pk_fma_f32 v[0:1], v[0:1], v[86:87], 1.0 op_sel_hi:[1,1,0]
	v_pk_fma_f32 v[2:3], v[2:3], v[84:85], 1.0 op_sel_hi:[1,1,0]
	v_pk_fma_f32 v[10:11], v[62:63], v[88:89], v[10:11] op_sel_hi:[0,1,1]
	s_waitcnt vmcnt(3)
	v_pk_fma_f32 v[8:9], v[14:15], v[8:9], v[94:95]
	s_waitcnt vmcnt(2)
	v_pk_fma_f32 v[14:15], v[18:19], v[82:83], v[96:97]
	v_pk_fma_f32 v[12:13], v[20:21], v[12:13], v[60:61]
	v_pk_fma_f32 v[10:11], v[16:17], v[10:11], v[26:27]
	v_pk_mul_f32 v[2:3], v[12:13], v[2:3]
	v_pk_mul_f32 v[0:1], v[14:15], v[0:1]
	v_pk_mul_f32 v[2:3], v[10:11], v[2:3]
	v_pk_mul_f32 v[0:1], v[8:9], v[0:1]
	s_waitcnt vmcnt(1)
	v_pk_mul_f32 v[2:3], v[24:25], v[2:3]
	v_pk_mul_f32 v[0:1], v[22:23], v[0:1]
	v_lshlrev_b32_e32 v98, 16, v66
	v_pk_mov_b32 v[8:9], v[0:1], v[2:3] op_sel:[1,0]
	v_mov_b32_e32 v1, v3
	v_pk_add_f32 v[0:1], v[8:9], v[0:1]
	v_and_b32_e32 v99, 0xffff0000, v66
	v_add_f32_e32 v0, v0, v1
	v_lshlrev_b32_e32 v66, 16, v67
	v_and_b32_e32 v67, 0xffff0000, v67
	v_add_f32_dpp v0, v0, v0 quad_perm:[1,0,3,2] row_mask:0xf bank_mask:0xf bound_ctrl:1
	v_lshlrev_b32_e32 v104, 16, v92
	v_and_b32_e32 v105, 0xffff0000, v92
	v_lshlrev_b32_e32 v92, 16, v93
	v_and_b32_e32 v93, 0xffff0000, v93
	v_xor_b32_e32 v85, 0x80000000, v67
	v_xor_b32_e32 v84, 0x80000000, v66
	v_xor_b32_e32 v87, 0x80000000, v99
	v_xor_b32_e32 v86, 0x80000000, v98
	v_add_f32_dpp v0, v0, v0 quad_perm:[2,3,0,1] row_mask:0xf bank_mask:0xf bound_ctrl:1
	v_pk_fma_f32 v[84:85], v[62:63], v[92:93], v[84:85] op_sel_hi:[0,1,1]
	v_pk_fma_f32 v[86:87], v[62:63], v[104:105], v[86:87] op_sel_hi:[0,1,1]
	v_add_f32_dpp v0, v0, v0 row_half_mirror row_mask:0xf bank_mask:0xf bound_ctrl:1
	s_waitcnt vmcnt(0)
	v_pk_fma_f32 v[16:17], v[78:79], v[86:87], v[98:99]
	v_pk_fma_f32 v[18:19], v[80:81], v[84:85], v[66:67]
	v_add_f32_dpp v0, v0, v0 row_mirror row_mask:0xf bank_mask:0xf bound_ctrl:1
	v_pk_fma_f32 v[2:3], v[18:19], v[0:1], v[6:7] op_sel_hi:[1,0,1]
	v_pk_fma_f32 v[0:1], v[16:17], v[0:1], v[4:5] op_sel_hi:[1,0,1]
	v_pk_mul_f32 v[2:3], v[2:3], v[70:71]
	v_pk_mul_f32 v[0:1], v[0:1], v[64:65]
	v_pk_fma_f32 v[2:3], v[2:3], v[72:73], v[76:77]
	v_pk_fma_f32 v[0:1], v[0:1], v[68:69], v[74:75]
	s_nop 0
	v_cvt_pk_bf16_f32 v0, v0, v1
	v_cvt_pk_bf16_f32 v1, v2, v3
	global_store_dwordx2 v[58:59], v[0:1], off offset:1536
	s_cbranch_scc0 .LBB0_1140
